# stack3 re-measure: attention fragment-read restructure + lazy rescale + GEMM M-phase entry trim
# speedup vs baseline: 1.0083x; 1.0083x over previous
; #define PG8_STAGE(bufoff, gbase, voff) do { _Pragma("unroll") for (int _i = 0; _i < 2; ++_i) \
;         __builtin_amdgcn_global_load_lds((const unsigned*)((const char*)(gbase) + (voff)[_i]), (PG8_LAS unsigned*)(lds + (bufoff) + ldsw + _i * 8192), 16, 0, 0); } while (0)
; #define PG8_LDA(dst, b, h) do { _Pragma("unroll") for (int m = 0; m < 4; ++m) _Pragma("unroll") for (int k = 0; k < 2; ++k) dst[m][k] = *(const PG8_LAS bf16x8*)(lds + PG8_SA(b, h) + aoff + m * 2048 + k * 1024); } while (0)
; #define PG8_LDB(dst, b, h) do { _Pragma("unroll") for (int n = 0; n < 2; ++n) _Pragma("unroll") for (int k = 0; k < 2; ++k) dst[n][k] = *(const PG8_LAS bf16x8*)(lds + PG8_SB(b, h) + boff + n * 2048 + k * 1024); } while (0)
; #define PG8_MMA(ai, bj, At, Bt) do { __builtin_amdgcn_s_setprio(1); _Pragma("unroll") for (int m = 0; m < 4; ++m) _Pragma("unroll") for (int n = 0; n < 2; ++n) _Pragma("unroll") for (int k = 0; k < 2; ++k) \
;         acc[ai][bj][m][n] = __builtin_amdgcn_mfma_f32_16x16x32_bf16(Bt[n][k], At[m][k], acc[ai][bj][m][n], 0, 0, 0); __builtin_amdgcn_s_setprio(0); } while (0)
; #define PG8_WAIT_V(n) asm volatile("s_waitcnt vmcnt(" #n ")" ::: "memory")
; #define PG8_WAIT_L(n) asm volatile("s_waitcnt lgkmcnt(" #n ")" ::: "memory")
; #define PG8_BAR __builtin_amdgcn_s_barrier()
; #define PG8_SCHED __builtin_amdgcn_sched_barrier(0)
; template <class Epi, class Sched, bool ALIGN_EPI = false, bool SP2 = false>
; __device__ __forceinline__ void gemm_phase(PG8_LAS unsigned char* lds, const Gemm g, const Sched& S, const Epi& E, const int tid) {
;     ...
;             PG8_LDB(B0, 0, 0); PG8_LDB(B1, 0, 1); PG8_SCHED; PG8_LDA(At, 0, 0); PG8_STAGE(PG8_SA(1, 1), a1 + hstep, voffA);
;             PG8_WAIT_V(8); PG8_WAIT_L(0); PG8_BAR; PG8_MMA(0, 0, At, B0); PG8_MMA(0, 1, At, B1); PG8_BAR; PG8_SCHED;
;             PG8_LDA(At, 0, 1); PG8_STAGE(PG8_SB(0, 0), b2, voffB); PG8_STAGE(PG8_SB(0, 1), b2 + hstep, voffB); PG8_STAGE(PG8_SA(0, 0), a2, voffA);
;             PG8_WAIT_V(8); PG8_WAIT_L(0); PG8_BAR; PG8_MMA(1, 0, At, B0); PG8_MMA(1, 1, At, B1); PG8_BAR; PG8_SCHED;
.LBB0_87:
	s_add_u32 s38, s22, s68
	s_addc_u32 s39, s23, s69
	s_add_u32 s38, s38, 0x100
	s_addc_u32 s39, s39, 0
	s_add_u32 s50, s89, s68
	s_addc_u32 s51, s90, s69
	s_add_i32 s92, 0, 0x10000
	s_cmpk_eq_i32 s68, 0x700
	s_cselect_b32 s73, s15, s39
	s_cselect_b32 s72, s86, s38
	v_add_u32_e32 v150, s92, v153
	s_cselect_b32 s71, s87, s51
	s_cselect_b32 s70, s88, s50
	s_add_i32 s38, 0, 0x14000
	ds_read_b128 v[170:173], v150
	ds_read_b128 v[174:177], v150 offset:1024
	ds_read_b128 v[178:181], v150 offset:2048
	ds_read_b128 v[182:185], v150 offset:3072
	v_add_u32_e32 v150, s38, v153
	ds_read_b128 v[186:189], v150
	ds_read_b128 v[190:193], v150 offset:1024
	ds_read_b128 v[206:209], v150 offset:2048
	ds_read_b128 v[210:213], v150 offset:3072
	v_lshl_add_u64 v[246:247], v[146:147], 0, s[68:69]
	s_add_i32 m0, s76, 0xc000
	ds_read_b128 v[214:217], v167
	ds_read_b128 v[218:221], v167 offset:1024
	ds_read_b128 v[222:225], v167 offset:2048
	ds_read_b128 v[226:229], v167 offset:3072
	ds_read_b128 v[230:233], v167 offset:4096
	ds_read_b128 v[234:237], v167 offset:5120
	ds_read_b128 v[238:241], v167 offset:6144
	ds_read_b128 v[242:245], v167 offset:7168
	global_load_lds_dwordx4 v[246:247], off
	v_lshl_add_u64 v[246:247], v[148:149], 0, s[68:69]
	s_add_i32 m0, s76, 0xe000
	s_nop 0
	global_load_lds_dwordx4 v[246:247], off
	s_waitcnt vmcnt(8)
	s_waitcnt lgkmcnt(0)
	s_setprio 1
	s_barrier
	v_mfma_f32_16x16x32_bf16 v[126:129], v[170:173], v[214:217], v[126:129]
	v_mfma_f32_16x16x32_bf16 v[122:125], v[178:181], v[214:217], v[122:125]
	v_mfma_f32_16x16x32_bf16 v[110:113], v[170:173], v[222:225], v[110:113]
	v_mfma_f32_16x16x32_bf16 v[106:109], v[178:181], v[222:225], v[106:109]
	v_mfma_f32_16x16x32_bf16 v[94:97], v[170:173], v[230:233], v[94:97]
	v_mfma_f32_16x16x32_bf16 v[90:93], v[178:181], v[230:233], v[90:93]
	v_mfma_f32_16x16x32_bf16 v[78:81], v[170:173], v[238:241], v[78:81]
	v_mfma_f32_16x16x32_bf16 v[74:77], v[178:181], v[238:241], v[74:77]
	v_mfma_f32_16x16x32_bf16 v[126:129], v[174:177], v[218:221], v[126:129]
	v_mfma_f32_16x16x32_bf16 v[122:125], v[182:185], v[218:221], v[122:125]
	v_mfma_f32_16x16x32_bf16 v[110:113], v[174:177], v[226:229], v[110:113]
	v_mfma_f32_16x16x32_bf16 v[106:109], v[182:185], v[226:229], v[106:109]
	v_mfma_f32_16x16x32_bf16 v[94:97], v[174:177], v[234:237], v[94:97]
	v_mfma_f32_16x16x32_bf16 v[90:93], v[182:185], v[234:237], v[90:93]
	v_mfma_f32_16x16x32_bf16 v[78:81], v[174:177], v[242:245], v[78:81]
	v_mfma_f32_16x16x32_bf16 v[74:77], v[182:185], v[242:245], v[74:77]
	v_mfma_f32_16x16x32_bf16 v[118:121], v[186:189], v[214:217], v[118:121]
	v_mfma_f32_16x16x32_bf16 v[114:117], v[206:209], v[214:217], v[114:117]
	v_mfma_f32_16x16x32_bf16 v[102:105], v[186:189], v[222:225], v[102:105]
	v_mfma_f32_16x16x32_bf16 v[98:101], v[206:209], v[222:225], v[98:101]
	v_mfma_f32_16x16x32_bf16 v[86:89], v[186:189], v[230:233], v[86:89]
	v_mfma_f32_16x16x32_bf16 v[82:85], v[206:209], v[230:233], v[82:85]
	v_mfma_f32_16x16x32_bf16 v[70:73], v[186:189], v[238:241], v[70:73]
	v_mfma_f32_16x16x32_bf16 v[66:69], v[206:209], v[238:241], v[66:69]
	v_mfma_f32_16x16x32_bf16 v[118:121], v[190:193], v[218:221], v[118:121]
	v_mfma_f32_16x16x32_bf16 v[114:117], v[210:213], v[218:221], v[114:117]
	v_mfma_f32_16x16x32_bf16 v[102:105], v[190:193], v[226:229], v[102:105]
	v_mfma_f32_16x16x32_bf16 v[98:101], v[210:213], v[226:229], v[98:101]
	v_mfma_f32_16x16x32_bf16 v[86:89], v[190:193], v[234:237], v[86:89]
	v_mfma_f32_16x16x32_bf16 v[82:85], v[210:213], v[234:237], v[82:85]
	v_mfma_f32_16x16x32_bf16 v[70:73], v[190:193], v[242:245], v[70:73]
	v_mfma_f32_16x16x32_bf16 v[66:69], v[210:213], v[242:245], v[66:69]
	s_setprio 0
	s_barrier
	s_add_i32 s39, s92, s75
	v_lshl_add_u64 v[246:247], s[70:71], 0, v[0:1]
	s_mov_b32 m0, s39
	ds_read_b128 v[214:217], v167 offset:16384
	ds_read_b128 v[218:221], v167 offset:17408
	ds_read_b128 v[222:225], v167 offset:18432
	ds_read_b128 v[226:229], v167 offset:19456
	ds_read_b128 v[230:233], v167 offset:20480
	ds_read_b128 v[234:237], v167 offset:21504
	ds_read_b128 v[238:241], v167 offset:22528
	ds_read_b128 v[242:245], v167 offset:23552
	global_load_lds_dwordx4 v[246:247], off
	s_add_i32 m0, s39, 0x2000
	s_add_u32 s50, s70, 0x40000
	v_lshl_add_u64 v[248:249], s[70:71], 0, v[130:131]
	s_addc_u32 s51, s71, 0
	s_add_i32 s38, s38, s75
	global_load_lds_dwordx4 v[248:249], off
	v_lshl_add_u64 v[250:251], s[50:51], 0, v[0:1]
	s_mov_b32 m0, s38
	v_lshl_add_u64 v[252:253], s[72:73], 0, v[132:133]
	global_load_lds_dwordx4 v[250:251], off
	v_lshl_add_u64 v[250:251], s[50:51], 0, v[130:131]
	s_add_i32 m0, s38, 0x2000
	s_nop 0
	global_load_lds_dwordx4 v[250:251], off
	v_lshl_add_u64 v[250:251], s[72:73], 0, v[134:135]
	s_mov_b32 m0, s76
	s_nop 0
	global_load_lds_dwordx4 v[250:251], off
	s_mov_b32 m0, s77
	s_nop 0
	global_load_lds_dwordx4 v[252:253], off
	s_waitcnt vmcnt(8)
	s_waitcnt lgkmcnt(0)
	s_setprio 1
	s_barrier
; #define PG8_STAGE(bufoff, gbase, voff) do { _Pragma("unroll") for (int _i = 0; _i < 2; ++_i) \
;         __builtin_amdgcn_global_load_lds((const unsigned*)((const char*)(gbase) + (voff)[_i]), (PG8_LAS unsigned*)(lds + (bufoff) + ldsw + _i * 8192), 16, 0, 0); } while (0)
; #define PG8_LDA(dst, b, h) do { _Pragma("unroll") for (int m = 0; m < 4; ++m) _Pragma("unroll") for (int k = 0; k < 2; ++k) dst[m][k] = *(const PG8_LAS bf16x8*)(lds + PG8_SA(b, h) + aoff + m * 2048 + k * 1024); } while (0)
; #define PG8_LDB(dst, b, h) do { _Pragma("unroll") for (int n = 0; n < 2; ++n) _Pragma("unroll") for (int k = 0; k < 2; ++k) dst[n][k] = *(const PG8_LAS bf16x8*)(lds + PG8_SB(b, h) + boff + n * 2048 + k * 1024); } while (0)
; #define PG8_MMA(ai, bj, At, Bt) do { __builtin_amdgcn_s_setprio(1); _Pragma("unroll") for (int m = 0; m < 4; ++m) _Pragma("unroll") for (int n = 0; n < 2; ++n) _Pragma("unroll") for (int k = 0; k < 2; ++k) \
;         acc[ai][bj][m][n] = __builtin_amdgcn_mfma_f32_16x16x32_bf16(Bt[n][k], At[m][k], acc[ai][bj][m][n], 0, 0, 0); __builtin_amdgcn_s_setprio(0); } while (0)
; #define PG8_WAIT_V(n) asm volatile("s_waitcnt vmcnt(" #n ")" ::: "memory")
; #define PG8_WAIT_L(n) asm volatile("s_waitcnt lgkmcnt(" #n ")" ::: "memory")
; #define PG8_BAR __builtin_amdgcn_s_barrier()
; #define PG8_SCHED __builtin_amdgcn_sched_barrier(0)
; template <class Epi, class Sched, bool ALIGN_EPI = false, bool SP2 = false>
; __device__ __forceinline__ void gemm_phase(PG8_LAS unsigned char* lds, const Gemm g, const Sched& S, const Epi& E, const int tid) {
;     ...
;             PG8_WAIT_V(8); PG8_WAIT_L(0); PG8_BAR; PG8_MMA(1, 0, At, B0); PG8_MMA(1, 1, At, B1); PG8_BAR; PG8_SCHED;
;             PG8_LDB(B0, 1, 0); PG8_LDB(B1, 1, 1); PG8_SCHED; PG8_LDA(At, 1, 0); PG8_STAGE(PG8_SA(0, 1), a2 + hstep, voffA);
;             PG8_WAIT_V(8); PG8_WAIT_L(0); PG8_BAR; PG8_MMA(0, 0, At, B0); PG8_MMA(0, 1, At, B1); PG8_BAR; PG8_SCHED;
	v_mfma_f32_16x16x32_bf16 v[62:65], v[170:173], v[214:217], v[62:65]
	v_mfma_f32_16x16x32_bf16 v[58:61], v[178:181], v[214:217], v[58:61]
	v_mfma_f32_16x16x32_bf16 v[46:49], v[170:173], v[222:225], v[46:49]
	v_mfma_f32_16x16x32_bf16 v[42:45], v[178:181], v[222:225], v[42:45]
	v_mfma_f32_16x16x32_bf16 v[30:33], v[170:173], v[230:233], v[30:33]
	v_mfma_f32_16x16x32_bf16 v[26:29], v[178:181], v[230:233], v[26:29]
	v_mfma_f32_16x16x32_bf16 v[14:17], v[170:173], v[238:241], v[14:17]
	v_mfma_f32_16x16x32_bf16 v[10:13], v[178:181], v[238:241], v[10:13]
	v_mfma_f32_16x16x32_bf16 v[62:65], v[174:177], v[218:221], v[62:65]
	v_mfma_f32_16x16x32_bf16 v[58:61], v[182:185], v[218:221], v[58:61]
	v_mfma_f32_16x16x32_bf16 v[46:49], v[174:177], v[226:229], v[46:49]
	v_mfma_f32_16x16x32_bf16 v[42:45], v[182:185], v[226:229], v[42:45]
	v_mfma_f32_16x16x32_bf16 v[30:33], v[174:177], v[234:237], v[30:33]
	v_mfma_f32_16x16x32_bf16 v[26:29], v[182:185], v[234:237], v[26:29]
	v_mfma_f32_16x16x32_bf16 v[14:17], v[174:177], v[242:245], v[14:17]
	v_mfma_f32_16x16x32_bf16 v[10:13], v[182:185], v[242:245], v[10:13]
	v_mfma_f32_16x16x32_bf16 v[54:57], v[186:189], v[214:217], v[54:57]
	v_mfma_f32_16x16x32_bf16 v[50:53], v[206:209], v[214:217], v[50:53]
	v_mfma_f32_16x16x32_bf16 v[38:41], v[186:189], v[222:225], v[38:41]
	v_mfma_f32_16x16x32_bf16 v[34:37], v[206:209], v[222:225], v[34:37]
	v_mfma_f32_16x16x32_bf16 v[22:25], v[186:189], v[230:233], v[22:25]
	v_mfma_f32_16x16x32_bf16 v[18:21], v[206:209], v[230:233], v[18:21]
	v_mfma_f32_16x16x32_bf16 v[6:9], v[186:189], v[238:241], v[6:9]
	v_mfma_f32_16x16x32_bf16 v[2:5], v[206:209], v[238:241], v[2:5]
	v_mfma_f32_16x16x32_bf16 v[54:57], v[190:193], v[218:221], v[54:57]
	v_mfma_f32_16x16x32_bf16 v[50:53], v[210:213], v[218:221], v[50:53]
	v_mfma_f32_16x16x32_bf16 v[38:41], v[190:193], v[226:229], v[38:41]
	v_mfma_f32_16x16x32_bf16 v[34:37], v[210:213], v[226:229], v[34:37]
	v_mfma_f32_16x16x32_bf16 v[22:25], v[190:193], v[234:237], v[22:25]
	v_mfma_f32_16x16x32_bf16 v[18:21], v[210:213], v[234:237], v[18:21]
	v_mfma_f32_16x16x32_bf16 v[6:9], v[190:193], v[242:245], v[6:9]
	v_mfma_f32_16x16x32_bf16 v[2:5], v[210:213], v[242:245], v[2:5]
	s_setprio 0
	s_barrier
	s_add_i32 s38, 0, 0x18000
	v_add_u32_e32 v150, s38, v153
	s_add_i32 s39, 0, 0x1c000
	ds_read_b128 v[170:173], v150
	ds_read_b128 v[174:177], v150 offset:1024
	ds_read_b128 v[178:181], v150 offset:2048
	ds_read_b128 v[182:185], v150 offset:3072
	v_add_u32_e32 v150, s39, v153
	ds_read_b128 v[186:189], v150
	ds_read_b128 v[190:193], v150 offset:1024
	ds_read_b128 v[206:209], v150 offset:2048
	ds_read_b128 v[210:213], v150 offset:3072
	s_add_u32 s50, s72, 0x40000
	s_addc_u32 s51, s73, 0
	s_mov_b32 m0, s78
	v_lshl_add_u64 v[194:195], s[50:51], 0, v[134:135]
	ds_read_b128 v[214:217], v167 offset:32768
	ds_read_b128 v[218:221], v167 offset:33792
	ds_read_b128 v[222:225], v167 offset:34816
	ds_read_b128 v[226:229], v167 offset:35840
	ds_read_b128 v[230:233], v167 offset:36864
	ds_read_b128 v[234:237], v167 offset:37888
	ds_read_b128 v[238:241], v167 offset:38912
	ds_read_b128 v[242:245], v167 offset:39936
	global_load_lds_dwordx4 v[194:195], off
	v_lshl_add_u64 v[194:195], s[50:51], 0, v[132:133]
	s_mov_b32 m0, s79
	s_nop 0
	global_load_lds_dwordx4 v[194:195], off
	s_waitcnt vmcnt(8)
	s_waitcnt lgkmcnt(0)
	s_setprio 1
	s_barrier
	v_mfma_f32_16x16x32_bf16 v[126:129], v[170:173], v[214:217], v[126:129]
	v_mfma_f32_16x16x32_bf16 v[122:125], v[178:181], v[214:217], v[122:125]
	v_mfma_f32_16x16x32_bf16 v[110:113], v[170:173], v[222:225], v[110:113]
	v_mfma_f32_16x16x32_bf16 v[106:109], v[178:181], v[222:225], v[106:109]
	v_mfma_f32_16x16x32_bf16 v[94:97], v[170:173], v[230:233], v[94:97]
	v_mfma_f32_16x16x32_bf16 v[90:93], v[178:181], v[230:233], v[90:93]
	v_mfma_f32_16x16x32_bf16 v[78:81], v[170:173], v[238:241], v[78:81]
	v_mfma_f32_16x16x32_bf16 v[74:77], v[178:181], v[238:241], v[74:77]
	v_mfma_f32_16x16x32_bf16 v[126:129], v[174:177], v[218:221], v[126:129]
	v_mfma_f32_16x16x32_bf16 v[122:125], v[182:185], v[218:221], v[122:125]
	v_mfma_f32_16x16x32_bf16 v[110:113], v[174:177], v[226:229], v[110:113]
	v_mfma_f32_16x16x32_bf16 v[106:109], v[182:185], v[226:229], v[106:109]
	v_mfma_f32_16x16x32_bf16 v[94:97], v[174:177], v[234:237], v[94:97]
	v_mfma_f32_16x16x32_bf16 v[90:93], v[182:185], v[234:237], v[90:93]
	v_mfma_f32_16x16x32_bf16 v[78:81], v[174:177], v[242:245], v[78:81]
	v_mfma_f32_16x16x32_bf16 v[74:77], v[182:185], v[242:245], v[74:77]
	v_mfma_f32_16x16x32_bf16 v[118:121], v[186:189], v[214:217], v[118:121]
	v_mfma_f32_16x16x32_bf16 v[114:117], v[206:209], v[214:217], v[114:117]
	v_mfma_f32_16x16x32_bf16 v[102:105], v[186:189], v[222:225], v[102:105]
	v_mfma_f32_16x16x32_bf16 v[98:101], v[206:209], v[222:225], v[98:101]
	v_mfma_f32_16x16x32_bf16 v[86:89], v[186:189], v[230:233], v[86:89]
	v_mfma_f32_16x16x32_bf16 v[82:85], v[206:209], v[230:233], v[82:85]
	v_mfma_f32_16x16x32_bf16 v[70:73], v[186:189], v[238:241], v[70:73]
	v_mfma_f32_16x16x32_bf16 v[66:69], v[206:209], v[238:241], v[66:69]
	v_mfma_f32_16x16x32_bf16 v[118:121], v[190:193], v[218:221], v[118:121]
	v_mfma_f32_16x16x32_bf16 v[114:117], v[210:213], v[218:221], v[114:117]
	v_mfma_f32_16x16x32_bf16 v[102:105], v[190:193], v[226:229], v[102:105]
	v_mfma_f32_16x16x32_bf16 v[98:101], v[210:213], v[226:229], v[98:101]
	v_mfma_f32_16x16x32_bf16 v[86:89], v[190:193], v[234:237], v[86:89]
	v_mfma_f32_16x16x32_bf16 v[82:85], v[210:213], v[234:237], v[82:85]
	v_mfma_f32_16x16x32_bf16 v[70:73], v[190:193], v[242:245], v[70:73]
	v_mfma_f32_16x16x32_bf16 v[66:69], v[210:213], v[242:245], v[66:69]
	s_setprio 0
	s_barrier
; #define PG8_STAGE(bufoff, gbase, voff) do { _Pragma("unroll") for (int _i = 0; _i < 2; ++_i) \
;         __builtin_amdgcn_global_load_lds((const unsigned*)((const char*)(gbase) + (voff)[_i]), (PG8_LAS unsigned*)(lds + (bufoff) + ldsw + _i * 8192), 16, 0, 0); } while (0)
; #define PG8_LDA(dst, b, h) do { _Pragma("unroll") for (int m = 0; m < 4; ++m) _Pragma("unroll") for (int k = 0; k < 2; ++k) dst[m][k] = *(const PG8_LAS bf16x8*)(lds + PG8_SA(b, h) + aoff + m * 2048 + k * 1024); } while (0)
; #define PG8_MMA(ai, bj, At, Bt) do { __builtin_amdgcn_s_setprio(1); _Pragma("unroll") for (int m = 0; m < 4; ++m) _Pragma("unroll") for (int n = 0; n < 2; ++n) _Pragma("unroll") for (int k = 0; k < 2; ++k) \
;         acc[ai][bj][m][n] = __builtin_amdgcn_mfma_f32_16x16x32_bf16(Bt[n][k], At[m][k], acc[ai][bj][m][n], 0, 0, 0); __builtin_amdgcn_s_setprio(0); } while (0)
; #define PG8_WAIT_V(n) asm volatile("s_waitcnt vmcnt(" #n ")" ::: "memory")
; #define PG8_WAIT_L(n) asm volatile("s_waitcnt lgkmcnt(" #n ")" ::: "memory")
; #define PG8_BAR __builtin_amdgcn_s_barrier()
; #define PG8_SCHED __builtin_amdgcn_sched_barrier(0)
; template <class Epi, class Sched, bool ALIGN_EPI = false, bool SP2 = false>
; __device__ __forceinline__ void gemm_phase(PG8_LAS unsigned char* lds, const Gemm g, const Sched& S, const Epi& E, const int tid) {
;     ...
;             PG8_LDA(At, 1, 1); PG8_STAGE(PG8_SB(1, 0), b3, voffB); PG8_STAGE(PG8_SB(1, 1), b3 + hstep, voffB); PG8_STAGE(PG8_SA(1, 0), a3, voffA);
;             PG8_WAIT_V(8); PG8_WAIT_L(0); PG8_BAR; PG8_MMA(1, 0, At, B0); PG8_MMA(1, 1, At, B1); PG8_BAR; PG8_SCHED;
	s_add_i32 s38, s38, s75
	v_lshl_add_u64 v[194:195], v[246:247], 0, s[56:57]
	s_mov_b32 m0, s38
	ds_read_b128 v[214:217], v167 offset:49152
	ds_read_b128 v[218:221], v167 offset:50176
	ds_read_b128 v[222:225], v167 offset:51200
	ds_read_b128 v[226:229], v167 offset:52224
	ds_read_b128 v[230:233], v167 offset:53248
	ds_read_b128 v[234:237], v167 offset:54272
	ds_read_b128 v[238:241], v167 offset:55296
	ds_read_b128 v[242:245], v167 offset:56320
	global_load_lds_dwordx4 v[194:195], off
	s_add_i32 m0, s38, 0x2000
	s_add_u32 s50, s70, 0x40080
	v_lshl_add_u64 v[194:195], v[248:249], 0, s[56:57]
	s_addc_u32 s51, s71, 0
	s_add_i32 s38, s39, s75
	global_load_lds_dwordx4 v[194:195], off
	v_lshl_add_u64 v[194:195], s[50:51], 0, v[0:1]
	s_mov_b32 m0, s38
	s_nop 0
	global_load_lds_dwordx4 v[194:195], off
	v_lshl_add_u64 v[194:195], s[50:51], 0, v[130:131]
	s_add_i32 m0, s38, 0x2000
	s_nop 0
	global_load_lds_dwordx4 v[194:195], off
	v_lshl_add_u64 v[194:195], v[250:251], 0, s[56:57]
	s_mov_b32 m0, s80
	s_nop 0
	global_load_lds_dwordx4 v[194:195], off
	v_lshl_add_u64 v[194:195], v[252:253], 0, s[56:57]
	s_mov_b32 m0, s81
	s_nop 0
	global_load_lds_dwordx4 v[194:195], off
	s_waitcnt vmcnt(8)
	s_waitcnt lgkmcnt(0)
	s_setprio 1
	s_barrier
	v_mfma_f32_16x16x32_bf16 v[62:65], v[170:173], v[214:217], v[62:65]
	v_mfma_f32_16x16x32_bf16 v[58:61], v[178:181], v[214:217], v[58:61]
	v_mfma_f32_16x16x32_bf16 v[46:49], v[170:173], v[222:225], v[46:49]
	v_mfma_f32_16x16x32_bf16 v[42:45], v[178:181], v[222:225], v[42:45]
	v_mfma_f32_16x16x32_bf16 v[30:33], v[170:173], v[230:233], v[30:33]
	v_mfma_f32_16x16x32_bf16 v[26:29], v[178:181], v[230:233], v[26:29]
	v_mfma_f32_16x16x32_bf16 v[14:17], v[170:173], v[238:241], v[14:17]
	v_mfma_f32_16x16x32_bf16 v[10:13], v[178:181], v[238:241], v[10:13]
	v_mfma_f32_16x16x32_bf16 v[62:65], v[174:177], v[218:221], v[62:65]
	v_mfma_f32_16x16x32_bf16 v[58:61], v[182:185], v[218:221], v[58:61]
	v_mfma_f32_16x16x32_bf16 v[46:49], v[174:177], v[226:229], v[46:49]
	v_mfma_f32_16x16x32_bf16 v[42:45], v[182:185], v[226:229], v[42:45]
	v_mfma_f32_16x16x32_bf16 v[30:33], v[174:177], v[234:237], v[30:33]
	v_mfma_f32_16x16x32_bf16 v[26:29], v[182:185], v[234:237], v[26:29]
	v_mfma_f32_16x16x32_bf16 v[14:17], v[174:177], v[242:245], v[14:17]
	v_mfma_f32_16x16x32_bf16 v[10:13], v[182:185], v[242:245], v[10:13]
	v_mfma_f32_16x16x32_bf16 v[54:57], v[186:189], v[214:217], v[54:57]
	v_mfma_f32_16x16x32_bf16 v[50:53], v[206:209], v[214:217], v[50:53]
	v_mfma_f32_16x16x32_bf16 v[38:41], v[186:189], v[222:225], v[38:41]
	v_mfma_f32_16x16x32_bf16 v[34:37], v[206:209], v[222:225], v[34:37]
	v_mfma_f32_16x16x32_bf16 v[22:25], v[186:189], v[230:233], v[22:25]
	v_mfma_f32_16x16x32_bf16 v[18:21], v[206:209], v[230:233], v[18:21]
	v_mfma_f32_16x16x32_bf16 v[6:9], v[186:189], v[238:241], v[6:9]
	v_mfma_f32_16x16x32_bf16 v[2:5], v[206:209], v[238:241], v[2:5]
	v_mfma_f32_16x16x32_bf16 v[54:57], v[190:193], v[218:221], v[54:57]
	v_mfma_f32_16x16x32_bf16 v[50:53], v[210:213], v[218:221], v[50:53]
	v_mfma_f32_16x16x32_bf16 v[38:41], v[190:193], v[226:229], v[38:41]
	v_mfma_f32_16x16x32_bf16 v[34:37], v[210:213], v[226:229], v[34:37]
	v_mfma_f32_16x16x32_bf16 v[22:25], v[190:193], v[234:237], v[22:25]
	v_mfma_f32_16x16x32_bf16 v[18:21], v[210:213], v[234:237], v[18:21]
	v_mfma_f32_16x16x32_bf16 v[6:9], v[190:193], v[242:245], v[6:9]
	v_mfma_f32_16x16x32_bf16 v[2:5], v[210:213], v[242:245], v[2:5]
	s_setprio 0
	s_barrier
	s_add_i32 s91, s91, 2
	s_add_u32 s68, s68, 0x100
	s_addc_u32 s69, s69, 0
	s_cmp_gt_u32 s91, 13
	s_cbranch_scc1 .LBB0_90

; #define PG8_STAGE(bufoff, gbase, voff) do { _Pragma("unroll") for (int _i = 0; _i < 2; ++_i) \
;         __builtin_amdgcn_global_load_lds((const unsigned*)((const char*)(gbase) + (voff)[_i]), (PG8_LAS unsigned*)(lds + (bufoff) + ldsw + _i * 8192), 16, 0, 0); } while (0)
; #define PG8_LDA(dst, b, h) do { _Pragma("unroll") for (int m = 0; m < 4; ++m) _Pragma("unroll") for (int k = 0; k < 2; ++k) dst[m][k] = *(const PG8_LAS bf16x8*)(lds + PG8_SA(b, h) + aoff + m * 2048 + k * 1024); } while (0)
; #define PG8_LDB(dst, b, h) do { _Pragma("unroll") for (int n = 0; n < 2; ++n) _Pragma("unroll") for (int k = 0; k < 2; ++k) dst[n][k] = *(const PG8_LAS bf16x8*)(lds + PG8_SB(b, h) + boff + n * 2048 + k * 1024); } while (0)
; #define PG8_MMA(ai, bj, At, Bt) do { __builtin_amdgcn_s_setprio(1); _Pragma("unroll") for (int m = 0; m < 4; ++m) _Pragma("unroll") for (int n = 0; n < 2; ++n) _Pragma("unroll") for (int k = 0; k < 2; ++k) \
;         acc[ai][bj][m][n] = __builtin_amdgcn_mfma_f32_16x16x32_bf16(Bt[n][k], At[m][k], acc[ai][bj][m][n], 0, 0, 0); __builtin_amdgcn_s_setprio(0); } while (0)
; #define PG8_WAIT_V(n) asm volatile("s_waitcnt vmcnt(" #n ")" ::: "memory")
; #define PG8_WAIT_L(n) asm volatile("s_waitcnt lgkmcnt(" #n ")" ::: "memory")
; #define PG8_BAR __builtin_amdgcn_s_barrier()
; #define PG8_SCHED __builtin_amdgcn_sched_barrier(0)
; template <class Epi, class Sched, bool ALIGN_EPI = false, bool SP2 = false>
; __device__ __forceinline__ void gemm_phase(PG8_LAS unsigned char* lds, const Gemm g, const Sched& S, const Epi& E, const int tid) {
;     ...
;             PG8_LDB(B0, 0, 0); PG8_LDB(B1, 0, 1); PG8_SCHED; PG8_LDA(At, 0, 0); PG8_STAGE(PG8_SA(1, 1), a1 + hstep, voffA);
;             PG8_WAIT_V(8); PG8_WAIT_L(0); PG8_BAR; PG8_MMA(0, 0, At, B0); PG8_MMA(0, 1, At, B1); PG8_BAR; PG8_SCHED;
;             PG8_LDA(At, 0, 1); PG8_STAGE(PG8_SB(0, 0), b2, voffB); PG8_STAGE(PG8_SB(0, 1), b2 + hstep, voffB); PG8_STAGE(PG8_SA(0, 0), a2, voffA);
;             PG8_WAIT_V(8); PG8_WAIT_L(0); PG8_BAR; PG8_MMA(1, 0, At, B0); PG8_MMA(1, 1, At, B1); PG8_BAR; PG8_SCHED;
.LBB0_208:
	s_add_u32 s38, s10, s12
	s_addc_u32 s39, s11, s13
	s_add_u32 s38, s38, 0x100
	s_addc_u32 s39, s39, 0
	s_add_u32 s51, vcc_lo, s12
	s_addc_u32 s74, vcc_hi, s13
	s_add_i32 s59, 0, 0x10000
	s_cmpk_eq_i32 s12, 0x700
	s_cselect_b32 s77, s49, s39
	s_cselect_b32 s76, s78, s38
	v_add_u32_e32 v0, s59, v153
	s_cselect_b32 s75, s69, s74
	s_cselect_b32 s74, s79, s51
	s_add_i32 s51, 0, 0x14000
	ds_read_b128 v[170:173], v0
	ds_read_b128 v[174:177], v0 offset:1024
	ds_read_b128 v[178:181], v0 offset:2048
	ds_read_b128 v[182:185], v0 offset:3072
	v_add_u32_e32 v0, s51, v153
	ds_read_b128 v[186:189], v0
	ds_read_b128 v[190:193], v0 offset:1024
	ds_read_b128 v[206:209], v0 offset:2048
	ds_read_b128 v[210:213], v0 offset:3072
	v_lshl_add_u64 v[194:195], v[148:149], 0, s[12:13]
	s_add_i32 m0, s84, 0xc000
	ds_read_b128 v[214:217], v167
	ds_read_b128 v[218:221], v167 offset:1024
	ds_read_b128 v[222:225], v167 offset:2048
	ds_read_b128 v[226:229], v167 offset:3072
	ds_read_b128 v[230:233], v167 offset:4096
	ds_read_b128 v[234:237], v167 offset:5120
	ds_read_b128 v[238:241], v167 offset:6144
	ds_read_b128 v[242:245], v167 offset:7168
	global_load_lds_dwordx4 v[194:195], off
	v_lshl_add_u64 v[194:195], v[150:151], 0, s[12:13]
	s_add_i32 m0, s84, 0xe000
	s_nop 0
	global_load_lds_dwordx4 v[194:195], off
	s_waitcnt vmcnt(8)
	s_waitcnt lgkmcnt(0)
	s_setprio 1
	s_barrier
	v_mfma_f32_16x16x32_bf16 v[126:129], v[170:173], v[214:217], v[126:129]
	v_mfma_f32_16x16x32_bf16 v[122:125], v[178:181], v[214:217], v[122:125]
	v_mfma_f32_16x16x32_bf16 v[110:113], v[170:173], v[222:225], v[110:113]
	v_mfma_f32_16x16x32_bf16 v[106:109], v[178:181], v[222:225], v[106:109]
	v_mfma_f32_16x16x32_bf16 v[94:97], v[170:173], v[230:233], v[94:97]
	v_mfma_f32_16x16x32_bf16 v[90:93], v[178:181], v[230:233], v[90:93]
	v_mfma_f32_16x16x32_bf16 v[78:81], v[170:173], v[238:241], v[78:81]
	v_mfma_f32_16x16x32_bf16 v[74:77], v[178:181], v[238:241], v[74:77]
	v_mfma_f32_16x16x32_bf16 v[126:129], v[174:177], v[218:221], v[126:129]
	v_mfma_f32_16x16x32_bf16 v[122:125], v[182:185], v[218:221], v[122:125]
	v_mfma_f32_16x16x32_bf16 v[110:113], v[174:177], v[226:229], v[110:113]
	v_mfma_f32_16x16x32_bf16 v[106:109], v[182:185], v[226:229], v[106:109]
	v_mfma_f32_16x16x32_bf16 v[94:97], v[174:177], v[234:237], v[94:97]
	v_mfma_f32_16x16x32_bf16 v[90:93], v[182:185], v[234:237], v[90:93]
	v_mfma_f32_16x16x32_bf16 v[78:81], v[174:177], v[242:245], v[78:81]
	v_mfma_f32_16x16x32_bf16 v[74:77], v[182:185], v[242:245], v[74:77]
	v_mfma_f32_16x16x32_bf16 v[118:121], v[186:189], v[214:217], v[118:121]
	v_mfma_f32_16x16x32_bf16 v[114:117], v[206:209], v[214:217], v[114:117]
	v_mfma_f32_16x16x32_bf16 v[102:105], v[186:189], v[222:225], v[102:105]
	v_mfma_f32_16x16x32_bf16 v[98:101], v[206:209], v[222:225], v[98:101]
	v_mfma_f32_16x16x32_bf16 v[86:89], v[186:189], v[230:233], v[86:89]
	v_mfma_f32_16x16x32_bf16 v[82:85], v[206:209], v[230:233], v[82:85]
	v_mfma_f32_16x16x32_bf16 v[70:73], v[186:189], v[238:241], v[70:73]
	v_mfma_f32_16x16x32_bf16 v[66:69], v[206:209], v[238:241], v[66:69]
	v_mfma_f32_16x16x32_bf16 v[118:121], v[190:193], v[218:221], v[118:121]
	v_mfma_f32_16x16x32_bf16 v[114:117], v[210:213], v[218:221], v[114:117]
	v_mfma_f32_16x16x32_bf16 v[102:105], v[190:193], v[226:229], v[102:105]
	v_mfma_f32_16x16x32_bf16 v[98:101], v[210:213], v[226:229], v[98:101]
	v_mfma_f32_16x16x32_bf16 v[86:89], v[190:193], v[234:237], v[86:89]
	v_mfma_f32_16x16x32_bf16 v[82:85], v[210:213], v[234:237], v[82:85]
	v_mfma_f32_16x16x32_bf16 v[70:73], v[190:193], v[242:245], v[70:73]
	v_mfma_f32_16x16x32_bf16 v[66:69], v[210:213], v[242:245], v[66:69]
	s_setprio 0
	s_barrier
	s_add_i32 s38, s59, s83
	v_lshl_add_u64 v[194:195], s[74:75], 0, v[134:135]
	s_mov_b32 m0, s38
	ds_read_b128 v[214:217], v167 offset:16384
	ds_read_b128 v[218:221], v167 offset:17408
	ds_read_b128 v[222:225], v167 offset:18432
	ds_read_b128 v[226:229], v167 offset:19456
	ds_read_b128 v[230:233], v167 offset:20480
	ds_read_b128 v[234:237], v167 offset:21504
	ds_read_b128 v[238:241], v167 offset:22528
	ds_read_b128 v[242:245], v167 offset:23552
	global_load_lds_dwordx4 v[194:195], off
	s_add_i32 m0, s38, 0x2000
	s_add_u32 s38, s74, 0x40000
	v_lshl_add_u64 v[246:247], s[74:75], 0, v[130:131]
	s_addc_u32 s39, s75, 0
	s_add_i32 s51, s51, s83
	global_load_lds_dwordx4 v[246:247], off
	v_lshl_add_u64 v[248:249], s[38:39], 0, v[134:135]
	s_mov_b32 m0, s51
	v_lshl_add_u64 v[250:251], s[76:77], 0, v[132:133]
	global_load_lds_dwordx4 v[248:249], off
	v_lshl_add_u64 v[248:249], s[38:39], 0, v[130:131]
	s_add_i32 m0, s51, 0x2000
	s_nop 0
	global_load_lds_dwordx4 v[248:249], off
	v_lshl_add_u64 v[248:249], s[76:77], 0, v[136:137]
	s_mov_b32 m0, s84
	s_nop 0
	global_load_lds_dwordx4 v[248:249], off
	s_mov_b32 m0, s85
	s_nop 0
	global_load_lds_dwordx4 v[250:251], off
	s_waitcnt vmcnt(8)
	s_waitcnt lgkmcnt(0)
	s_setprio 1
	s_barrier
; #define PG8_STAGE(bufoff, gbase, voff) do { _Pragma("unroll") for (int _i = 0; _i < 2; ++_i) \
;         __builtin_amdgcn_global_load_lds((const unsigned*)((const char*)(gbase) + (voff)[_i]), (PG8_LAS unsigned*)(lds + (bufoff) + ldsw + _i * 8192), 16, 0, 0); } while (0)
; #define PG8_LDA(dst, b, h) do { _Pragma("unroll") for (int m = 0; m < 4; ++m) _Pragma("unroll") for (int k = 0; k < 2; ++k) dst[m][k] = *(const PG8_LAS bf16x8*)(lds + PG8_SA(b, h) + aoff + m * 2048 + k * 1024); } while (0)
; #define PG8_LDB(dst, b, h) do { _Pragma("unroll") for (int n = 0; n < 2; ++n) _Pragma("unroll") for (int k = 0; k < 2; ++k) dst[n][k] = *(const PG8_LAS bf16x8*)(lds + PG8_SB(b, h) + boff + n * 2048 + k * 1024); } while (0)
; #define PG8_MMA(ai, bj, At, Bt) do { __builtin_amdgcn_s_setprio(1); _Pragma("unroll") for (int m = 0; m < 4; ++m) _Pragma("unroll") for (int n = 0; n < 2; ++n) _Pragma("unroll") for (int k = 0; k < 2; ++k) \
;         acc[ai][bj][m][n] = __builtin_amdgcn_mfma_f32_16x16x32_bf16(Bt[n][k], At[m][k], acc[ai][bj][m][n], 0, 0, 0); __builtin_amdgcn_s_setprio(0); } while (0)
; #define PG8_WAIT_V(n) asm volatile("s_waitcnt vmcnt(" #n ")" ::: "memory")
; #define PG8_WAIT_L(n) asm volatile("s_waitcnt lgkmcnt(" #n ")" ::: "memory")
; #define PG8_BAR __builtin_amdgcn_s_barrier()
; #define PG8_SCHED __builtin_amdgcn_sched_barrier(0)
; template <class Epi, class Sched, bool ALIGN_EPI = false, bool SP2 = false>
; __device__ __forceinline__ void gemm_phase(PG8_LAS unsigned char* lds, const Gemm g, const Sched& S, const Epi& E, const int tid) {
;     ...
;             PG8_WAIT_V(8); PG8_WAIT_L(0); PG8_BAR; PG8_MMA(1, 0, At, B0); PG8_MMA(1, 1, At, B1); PG8_BAR; PG8_SCHED;
;             PG8_LDB(B0, 1, 0); PG8_LDB(B1, 1, 1); PG8_SCHED; PG8_LDA(At, 1, 0); PG8_STAGE(PG8_SA(0, 1), a2 + hstep, voffA);
;             PG8_WAIT_V(8); PG8_WAIT_L(0); PG8_BAR; PG8_MMA(0, 0, At, B0); PG8_MMA(0, 1, At, B1); PG8_BAR; PG8_SCHED;
	v_mfma_f32_16x16x32_bf16 v[62:65], v[170:173], v[214:217], v[62:65]
	v_mfma_f32_16x16x32_bf16 v[58:61], v[178:181], v[214:217], v[58:61]
	v_mfma_f32_16x16x32_bf16 v[46:49], v[170:173], v[222:225], v[46:49]
	v_mfma_f32_16x16x32_bf16 v[42:45], v[178:181], v[222:225], v[42:45]
	v_mfma_f32_16x16x32_bf16 v[30:33], v[170:173], v[230:233], v[30:33]
	v_mfma_f32_16x16x32_bf16 v[26:29], v[178:181], v[230:233], v[26:29]
	v_mfma_f32_16x16x32_bf16 v[14:17], v[170:173], v[238:241], v[14:17]
	v_mfma_f32_16x16x32_bf16 v[10:13], v[178:181], v[238:241], v[10:13]
	v_mfma_f32_16x16x32_bf16 v[62:65], v[174:177], v[218:221], v[62:65]
	v_mfma_f32_16x16x32_bf16 v[58:61], v[182:185], v[218:221], v[58:61]
	v_mfma_f32_16x16x32_bf16 v[46:49], v[174:177], v[226:229], v[46:49]
	v_mfma_f32_16x16x32_bf16 v[42:45], v[182:185], v[226:229], v[42:45]
	v_mfma_f32_16x16x32_bf16 v[30:33], v[174:177], v[234:237], v[30:33]
	v_mfma_f32_16x16x32_bf16 v[26:29], v[182:185], v[234:237], v[26:29]
	v_mfma_f32_16x16x32_bf16 v[14:17], v[174:177], v[242:245], v[14:17]
	v_mfma_f32_16x16x32_bf16 v[10:13], v[182:185], v[242:245], v[10:13]
	v_mfma_f32_16x16x32_bf16 v[54:57], v[186:189], v[214:217], v[54:57]
	v_mfma_f32_16x16x32_bf16 v[50:53], v[206:209], v[214:217], v[50:53]
	v_mfma_f32_16x16x32_bf16 v[38:41], v[186:189], v[222:225], v[38:41]
	v_mfma_f32_16x16x32_bf16 v[34:37], v[206:209], v[222:225], v[34:37]
	v_mfma_f32_16x16x32_bf16 v[22:25], v[186:189], v[230:233], v[22:25]
	v_mfma_f32_16x16x32_bf16 v[18:21], v[206:209], v[230:233], v[18:21]
	v_mfma_f32_16x16x32_bf16 v[6:9], v[186:189], v[238:241], v[6:9]
	v_mfma_f32_16x16x32_bf16 v[2:5], v[206:209], v[238:241], v[2:5]
	v_mfma_f32_16x16x32_bf16 v[54:57], v[190:193], v[218:221], v[54:57]
	v_mfma_f32_16x16x32_bf16 v[50:53], v[210:213], v[218:221], v[50:53]
	v_mfma_f32_16x16x32_bf16 v[38:41], v[190:193], v[226:229], v[38:41]
	v_mfma_f32_16x16x32_bf16 v[34:37], v[210:213], v[226:229], v[34:37]
	v_mfma_f32_16x16x32_bf16 v[22:25], v[190:193], v[234:237], v[22:25]
	v_mfma_f32_16x16x32_bf16 v[18:21], v[210:213], v[234:237], v[18:21]
	v_mfma_f32_16x16x32_bf16 v[6:9], v[190:193], v[242:245], v[6:9]
	v_mfma_f32_16x16x32_bf16 v[2:5], v[210:213], v[242:245], v[2:5]
	s_setprio 0
	s_barrier
	s_add_i32 s51, 0, 0x18000
	v_add_u32_e32 v0, s51, v153
	s_add_i32 s59, 0, 0x1c000
	ds_read_b128 v[170:173], v0
	ds_read_b128 v[174:177], v0 offset:1024
	ds_read_b128 v[178:181], v0 offset:2048
	ds_read_b128 v[182:185], v0 offset:3072
	v_add_u32_e32 v0, s59, v153
	ds_read_b128 v[186:189], v0
	ds_read_b128 v[190:193], v0 offset:1024
	ds_read_b128 v[206:209], v0 offset:2048
	ds_read_b128 v[210:213], v0 offset:3072
	s_add_u32 s38, s76, 0x40000
	s_addc_u32 s39, s77, 0
	s_mov_b32 m0, s86
	v_lshl_add_u64 v[252:253], s[38:39], 0, v[136:137]
	ds_read_b128 v[214:217], v167 offset:32768
	ds_read_b128 v[218:221], v167 offset:33792
	ds_read_b128 v[222:225], v167 offset:34816
	ds_read_b128 v[226:229], v167 offset:35840
	ds_read_b128 v[230:233], v167 offset:36864
	ds_read_b128 v[234:237], v167 offset:37888
	ds_read_b128 v[238:241], v167 offset:38912
	ds_read_b128 v[242:245], v167 offset:39936
	global_load_lds_dwordx4 v[252:253], off
	v_lshl_add_u64 v[252:253], s[38:39], 0, v[132:133]
	s_mov_b32 m0, s87
	s_nop 0
	global_load_lds_dwordx4 v[252:253], off
	s_waitcnt vmcnt(8)
	s_waitcnt lgkmcnt(0)
	s_setprio 1
	s_barrier
	v_mfma_f32_16x16x32_bf16 v[126:129], v[170:173], v[214:217], v[126:129]
	v_mfma_f32_16x16x32_bf16 v[122:125], v[178:181], v[214:217], v[122:125]
	v_mfma_f32_16x16x32_bf16 v[110:113], v[170:173], v[222:225], v[110:113]
	v_mfma_f32_16x16x32_bf16 v[106:109], v[178:181], v[222:225], v[106:109]
	v_mfma_f32_16x16x32_bf16 v[94:97], v[170:173], v[230:233], v[94:97]
	v_mfma_f32_16x16x32_bf16 v[90:93], v[178:181], v[230:233], v[90:93]
	v_mfma_f32_16x16x32_bf16 v[78:81], v[170:173], v[238:241], v[78:81]
	v_mfma_f32_16x16x32_bf16 v[74:77], v[178:181], v[238:241], v[74:77]
	v_mfma_f32_16x16x32_bf16 v[126:129], v[174:177], v[218:221], v[126:129]
	v_mfma_f32_16x16x32_bf16 v[122:125], v[182:185], v[218:221], v[122:125]
	v_mfma_f32_16x16x32_bf16 v[110:113], v[174:177], v[226:229], v[110:113]
	v_mfma_f32_16x16x32_bf16 v[106:109], v[182:185], v[226:229], v[106:109]
	v_mfma_f32_16x16x32_bf16 v[94:97], v[174:177], v[234:237], v[94:97]
	v_mfma_f32_16x16x32_bf16 v[90:93], v[182:185], v[234:237], v[90:93]
	v_mfma_f32_16x16x32_bf16 v[78:81], v[174:177], v[242:245], v[78:81]
	v_mfma_f32_16x16x32_bf16 v[74:77], v[182:185], v[242:245], v[74:77]
	v_mfma_f32_16x16x32_bf16 v[118:121], v[186:189], v[214:217], v[118:121]
	v_mfma_f32_16x16x32_bf16 v[114:117], v[206:209], v[214:217], v[114:117]
	v_mfma_f32_16x16x32_bf16 v[102:105], v[186:189], v[222:225], v[102:105]
	v_mfma_f32_16x16x32_bf16 v[98:101], v[206:209], v[222:225], v[98:101]
	v_mfma_f32_16x16x32_bf16 v[86:89], v[186:189], v[230:233], v[86:89]
	v_mfma_f32_16x16x32_bf16 v[82:85], v[206:209], v[230:233], v[82:85]
	v_mfma_f32_16x16x32_bf16 v[70:73], v[186:189], v[238:241], v[70:73]
	v_mfma_f32_16x16x32_bf16 v[66:69], v[206:209], v[238:241], v[66:69]
	v_mfma_f32_16x16x32_bf16 v[118:121], v[190:193], v[218:221], v[118:121]
	v_mfma_f32_16x16x32_bf16 v[114:117], v[210:213], v[218:221], v[114:117]
	v_mfma_f32_16x16x32_bf16 v[102:105], v[190:193], v[226:229], v[102:105]
	v_mfma_f32_16x16x32_bf16 v[98:101], v[210:213], v[226:229], v[98:101]
	v_mfma_f32_16x16x32_bf16 v[86:89], v[190:193], v[234:237], v[86:89]
	v_mfma_f32_16x16x32_bf16 v[82:85], v[210:213], v[234:237], v[82:85]
	v_mfma_f32_16x16x32_bf16 v[70:73], v[190:193], v[242:245], v[70:73]
	v_mfma_f32_16x16x32_bf16 v[66:69], v[210:213], v[242:245], v[66:69]
	s_setprio 0
	s_barrier
; #define PG8_STAGE(bufoff, gbase, voff) do { _Pragma("unroll") for (int _i = 0; _i < 2; ++_i) \
;         __builtin_amdgcn_global_load_lds((const unsigned*)((const char*)(gbase) + (voff)[_i]), (PG8_LAS unsigned*)(lds + (bufoff) + ldsw + _i * 8192), 16, 0, 0); } while (0)
; #define PG8_LDA(dst, b, h) do { _Pragma("unroll") for (int m = 0; m < 4; ++m) _Pragma("unroll") for (int k = 0; k < 2; ++k) dst[m][k] = *(const PG8_LAS bf16x8*)(lds + PG8_SA(b, h) + aoff + m * 2048 + k * 1024); } while (0)
; #define PG8_MMA(ai, bj, At, Bt) do { __builtin_amdgcn_s_setprio(1); _Pragma("unroll") for (int m = 0; m < 4; ++m) _Pragma("unroll") for (int n = 0; n < 2; ++n) _Pragma("unroll") for (int k = 0; k < 2; ++k) \
;         acc[ai][bj][m][n] = __builtin_amdgcn_mfma_f32_16x16x32_bf16(Bt[n][k], At[m][k], acc[ai][bj][m][n], 0, 0, 0); __builtin_amdgcn_s_setprio(0); } while (0)
; #define PG8_WAIT_V(n) asm volatile("s_waitcnt vmcnt(" #n ")" ::: "memory")
; #define PG8_WAIT_L(n) asm volatile("s_waitcnt lgkmcnt(" #n ")" ::: "memory")
; #define PG8_BAR __builtin_amdgcn_s_barrier()
; #define PG8_SCHED __builtin_amdgcn_sched_barrier(0)
; template <class Epi, class Sched, bool ALIGN_EPI = false, bool SP2 = false>
; __device__ __forceinline__ void gemm_phase(PG8_LAS unsigned char* lds, const Gemm g, const Sched& S, const Epi& E, const int tid) {
;     ...
;             PG8_LDA(At, 1, 1); PG8_STAGE(PG8_SB(1, 0), b3, voffB); PG8_STAGE(PG8_SB(1, 1), b3 + hstep, voffB); PG8_STAGE(PG8_SA(1, 0), a3, voffA);
;             PG8_WAIT_V(8); PG8_WAIT_L(0); PG8_BAR; PG8_MMA(1, 0, At, B0); PG8_MMA(1, 1, At, B1); PG8_BAR; PG8_SCHED;
	s_add_i32 s38, s51, s83
	v_lshl_add_u64 v[194:195], v[194:195], 0, s[56:57]
	s_mov_b32 m0, s38
	ds_read_b128 v[214:217], v167 offset:49152
	ds_read_b128 v[218:221], v167 offset:50176
	ds_read_b128 v[222:225], v167 offset:51200
	ds_read_b128 v[226:229], v167 offset:52224
	ds_read_b128 v[230:233], v167 offset:53248
	ds_read_b128 v[234:237], v167 offset:54272
	ds_read_b128 v[238:241], v167 offset:55296
	ds_read_b128 v[242:245], v167 offset:56320
	global_load_lds_dwordx4 v[194:195], off
	s_add_i32 m0, s38, 0x2000
	s_add_u32 s38, s74, 0x40080
	v_lshl_add_u64 v[194:195], v[246:247], 0, s[56:57]
	s_addc_u32 s39, s75, 0
	s_add_i32 s51, s59, s83
	global_load_lds_dwordx4 v[194:195], off
	v_lshl_add_u64 v[194:195], s[38:39], 0, v[134:135]
	s_mov_b32 m0, s51
	s_nop 0
	global_load_lds_dwordx4 v[194:195], off
	v_lshl_add_u64 v[194:195], s[38:39], 0, v[130:131]
	s_add_i32 m0, s51, 0x2000
	s_nop 0
	global_load_lds_dwordx4 v[194:195], off
	v_lshl_add_u64 v[194:195], v[248:249], 0, s[56:57]
	s_mov_b32 m0, s88
	s_nop 0
	global_load_lds_dwordx4 v[194:195], off
	v_lshl_add_u64 v[194:195], v[250:251], 0, s[56:57]
	s_mov_b32 m0, s89
	s_nop 0
	global_load_lds_dwordx4 v[194:195], off
	s_waitcnt vmcnt(8)
	s_waitcnt lgkmcnt(0)
	s_setprio 1
	s_barrier
	v_mfma_f32_16x16x32_bf16 v[62:65], v[170:173], v[214:217], v[62:65]
	v_mfma_f32_16x16x32_bf16 v[58:61], v[178:181], v[214:217], v[58:61]
	v_mfma_f32_16x16x32_bf16 v[46:49], v[170:173], v[222:225], v[46:49]
	v_mfma_f32_16x16x32_bf16 v[42:45], v[178:181], v[222:225], v[42:45]
	v_mfma_f32_16x16x32_bf16 v[30:33], v[170:173], v[230:233], v[30:33]
	v_mfma_f32_16x16x32_bf16 v[26:29], v[178:181], v[230:233], v[26:29]
	v_mfma_f32_16x16x32_bf16 v[14:17], v[170:173], v[238:241], v[14:17]
	v_mfma_f32_16x16x32_bf16 v[10:13], v[178:181], v[238:241], v[10:13]
	v_mfma_f32_16x16x32_bf16 v[62:65], v[174:177], v[218:221], v[62:65]
	v_mfma_f32_16x16x32_bf16 v[58:61], v[182:185], v[218:221], v[58:61]
	v_mfma_f32_16x16x32_bf16 v[46:49], v[174:177], v[226:229], v[46:49]
	v_mfma_f32_16x16x32_bf16 v[42:45], v[182:185], v[226:229], v[42:45]
	v_mfma_f32_16x16x32_bf16 v[30:33], v[174:177], v[234:237], v[30:33]
	v_mfma_f32_16x16x32_bf16 v[26:29], v[182:185], v[234:237], v[26:29]
	v_mfma_f32_16x16x32_bf16 v[14:17], v[174:177], v[242:245], v[14:17]
	v_mfma_f32_16x16x32_bf16 v[10:13], v[182:185], v[242:245], v[10:13]
	v_mfma_f32_16x16x32_bf16 v[54:57], v[186:189], v[214:217], v[54:57]
	v_mfma_f32_16x16x32_bf16 v[50:53], v[206:209], v[214:217], v[50:53]
	v_mfma_f32_16x16x32_bf16 v[38:41], v[186:189], v[222:225], v[38:41]
	v_mfma_f32_16x16x32_bf16 v[34:37], v[206:209], v[222:225], v[34:37]
	v_mfma_f32_16x16x32_bf16 v[22:25], v[186:189], v[230:233], v[22:25]
	v_mfma_f32_16x16x32_bf16 v[18:21], v[206:209], v[230:233], v[18:21]
	v_mfma_f32_16x16x32_bf16 v[6:9], v[186:189], v[238:241], v[6:9]
	v_mfma_f32_16x16x32_bf16 v[2:5], v[206:209], v[238:241], v[2:5]
	v_mfma_f32_16x16x32_bf16 v[54:57], v[190:193], v[218:221], v[54:57]
	v_mfma_f32_16x16x32_bf16 v[50:53], v[210:213], v[218:221], v[50:53]
	v_mfma_f32_16x16x32_bf16 v[38:41], v[190:193], v[226:229], v[38:41]
	v_mfma_f32_16x16x32_bf16 v[34:37], v[210:213], v[226:229], v[34:37]
	v_mfma_f32_16x16x32_bf16 v[22:25], v[190:193], v[234:237], v[22:25]
	v_mfma_f32_16x16x32_bf16 v[18:21], v[210:213], v[234:237], v[18:21]
	v_mfma_f32_16x16x32_bf16 v[6:9], v[190:193], v[242:245], v[6:9]
	v_mfma_f32_16x16x32_bf16 v[2:5], v[210:213], v[242:245], v[2:5]
	s_setprio 0
	s_barrier
	s_add_i32 s50, s50, 2
	s_add_u32 s12, s12, 0x100
	s_addc_u32 s13, s13, 0
	s_cmp_gt_u32 s50, 13
	s_cbranch_scc1 .LBB0_211

; #define PG8_STAGE(bufoff, gbase, voff) do { _Pragma("unroll") for (int _i = 0; _i < 2; ++_i) \
;         __builtin_amdgcn_global_load_lds((const unsigned*)((const char*)(gbase) + (voff)[_i]), (PG8_LAS unsigned*)(lds + (bufoff) + ldsw + _i * 8192), 16, 0, 0); } while (0)
; #define PG8_LDA(dst, b, h) do { _Pragma("unroll") for (int m = 0; m < 4; ++m) _Pragma("unroll") for (int k = 0; k < 2; ++k) dst[m][k] = *(const PG8_LAS bf16x8*)(lds + PG8_SA(b, h) + aoff + m * 2048 + k * 1024); } while (0)
; #define PG8_LDB(dst, b, h) do { _Pragma("unroll") for (int n = 0; n < 2; ++n) _Pragma("unroll") for (int k = 0; k < 2; ++k) dst[n][k] = *(const PG8_LAS bf16x8*)(lds + PG8_SB(b, h) + boff + n * 2048 + k * 1024); } while (0)
; #define PG8_MMA(ai, bj, At, Bt) do { __builtin_amdgcn_s_setprio(1); _Pragma("unroll") for (int m = 0; m < 4; ++m) _Pragma("unroll") for (int n = 0; n < 2; ++n) _Pragma("unroll") for (int k = 0; k < 2; ++k) \
;         acc[ai][bj][m][n] = __builtin_amdgcn_mfma_f32_16x16x32_bf16(Bt[n][k], At[m][k], acc[ai][bj][m][n], 0, 0, 0); __builtin_amdgcn_s_setprio(0); } while (0)
; #define PG8_WAIT_V(n) asm volatile("s_waitcnt vmcnt(" #n ")" ::: "memory")
; #define PG8_WAIT_L(n) asm volatile("s_waitcnt lgkmcnt(" #n ")" ::: "memory")
; #define PG8_BAR __builtin_amdgcn_s_barrier()
; #define PG8_SCHED __builtin_amdgcn_sched_barrier(0)
; template <class Epi, class Sched, bool ALIGN_EPI = false, bool SP2 = false>
; __device__ __forceinline__ void gemm_phase(PG8_LAS unsigned char* lds, const Gemm g, const Sched& S, const Epi& E, const int tid) {
;     ...
;             PG8_LDB(B0, 0, 0); PG8_LDB(B1, 0, 1); PG8_SCHED; PG8_LDA(At, 0, 0); PG8_STAGE(PG8_SA(1, 1), a1 + hstep, voffA);
;             PG8_WAIT_V(8); PG8_WAIT_L(0); PG8_BAR; PG8_MMA(0, 0, At, B0); PG8_MMA(0, 1, At, B1); PG8_BAR; PG8_SCHED;
;             PG8_LDA(At, 0, 1); PG8_STAGE(PG8_SB(0, 0), b2, voffB); PG8_STAGE(PG8_SB(0, 1), b2 + hstep, voffB); PG8_STAGE(PG8_SA(0, 0), a2, voffA);
;             PG8_WAIT_V(8); PG8_WAIT_L(0); PG8_BAR; PG8_MMA(1, 0, At, B0); PG8_MMA(1, 1, At, B1); PG8_BAR; PG8_SCHED;
.LBB0_618:
	s_add_i32 s85, s70, 2
	s_add_u32 s38, s68, 0x80
	s_addc_u32 s39, s69, 0
	s_add_i32 s59, 0, 0x10000
	s_cmp_eq_u32 s81, s70
	s_cselect_b32 s71, s11, s39
	s_cselect_b32 s70, s10, s38
	s_cselect_b32 s39, s67, s51
	s_cselect_b32 s38, s66, s50
	s_add_i32 s86, 0, 0x14000
	v_add_u32_e32 v142, s59, v205
	v_add_u32_e32 v180, s86, v205
	ds_read_b128 v[130:133], v142
	ds_read_b128 v[134:137], v142 offset:1024
	ds_read_b128 v[138:141], v142 offset:2048
	ds_read_b128 v[142:145], v142 offset:3072
	ds_read_b128 v[146:149], v180
	ds_read_b128 v[150:153], v180 offset:1024
	ds_read_b128 v[176:179], v180 offset:2048
	ds_read_b128 v[180:183], v180 offset:3072
	v_lshl_add_u64 v[192:193], s[68:69], 0, v[172:173]
	s_add_i32 m0, s73, 0xc000
	ds_read_b128 v[184:187], v207
	ds_read_b128 v[188:191], v207 offset:1024
	ds_read_b128 v[208:211], v207 offset:2048
	ds_read_b128 v[212:215], v207 offset:3072
	ds_read_b128 v[216:219], v207 offset:4096
	ds_read_b128 v[220:223], v207 offset:5120
	ds_read_b128 v[224:227], v207 offset:6144
	ds_read_b128 v[228:231], v207 offset:7168
	global_load_lds_dwordx4 v[192:193], off
	v_lshl_add_u64 v[192:193], s[68:69], 0, v[174:175]
	s_add_i32 m0, s73, 0xe000
	s_nop 0
	global_load_lds_dwordx4 v[192:193], off
	s_waitcnt vmcnt(8)
	s_waitcnt lgkmcnt(0)
	s_setprio 1
	s_barrier
	v_mfma_f32_16x16x32_bf16 v[126:129], v[130:133], v[184:187], v[126:129]
	v_mfma_f32_16x16x32_bf16 v[122:125], v[138:141], v[184:187], v[122:125]
	v_mfma_f32_16x16x32_bf16 v[110:113], v[130:133], v[208:211], v[110:113]
	v_mfma_f32_16x16x32_bf16 v[106:109], v[138:141], v[208:211], v[106:109]
	v_mfma_f32_16x16x32_bf16 v[94:97], v[130:133], v[216:219], v[94:97]
	v_mfma_f32_16x16x32_bf16 v[90:93], v[138:141], v[216:219], v[90:93]
	v_mfma_f32_16x16x32_bf16 v[78:81], v[130:133], v[224:227], v[78:81]
	v_mfma_f32_16x16x32_bf16 v[74:77], v[138:141], v[224:227], v[74:77]
	v_mfma_f32_16x16x32_bf16 v[126:129], v[134:137], v[188:191], v[126:129]
	v_mfma_f32_16x16x32_bf16 v[122:125], v[142:145], v[188:191], v[122:125]
	v_mfma_f32_16x16x32_bf16 v[110:113], v[134:137], v[212:215], v[110:113]
	v_mfma_f32_16x16x32_bf16 v[106:109], v[142:145], v[212:215], v[106:109]
	v_mfma_f32_16x16x32_bf16 v[94:97], v[134:137], v[220:223], v[94:97]
	v_mfma_f32_16x16x32_bf16 v[90:93], v[142:145], v[220:223], v[90:93]
	v_mfma_f32_16x16x32_bf16 v[78:81], v[134:137], v[228:231], v[78:81]
	v_mfma_f32_16x16x32_bf16 v[74:77], v[142:145], v[228:231], v[74:77]
	v_mfma_f32_16x16x32_bf16 v[118:121], v[146:149], v[184:187], v[118:121]
	v_mfma_f32_16x16x32_bf16 v[114:117], v[176:179], v[184:187], v[114:117]
	v_mfma_f32_16x16x32_bf16 v[102:105], v[146:149], v[208:211], v[102:105]
	v_mfma_f32_16x16x32_bf16 v[98:101], v[176:179], v[208:211], v[98:101]
	v_mfma_f32_16x16x32_bf16 v[86:89], v[146:149], v[216:219], v[86:89]
	v_mfma_f32_16x16x32_bf16 v[82:85], v[176:179], v[216:219], v[82:85]
	v_mfma_f32_16x16x32_bf16 v[70:73], v[146:149], v[224:227], v[70:73]
	v_mfma_f32_16x16x32_bf16 v[66:69], v[176:179], v[224:227], v[66:69]
	v_mfma_f32_16x16x32_bf16 v[118:121], v[150:153], v[188:191], v[118:121]
	v_mfma_f32_16x16x32_bf16 v[114:117], v[180:183], v[188:191], v[114:117]
	v_mfma_f32_16x16x32_bf16 v[102:105], v[150:153], v[212:215], v[102:105]
	v_mfma_f32_16x16x32_bf16 v[98:101], v[180:183], v[212:215], v[98:101]
	v_mfma_f32_16x16x32_bf16 v[86:89], v[150:153], v[220:223], v[86:89]
	v_mfma_f32_16x16x32_bf16 v[82:85], v[180:183], v[220:223], v[82:85]
	v_mfma_f32_16x16x32_bf16 v[70:73], v[150:153], v[228:231], v[70:73]
	v_mfma_f32_16x16x32_bf16 v[66:69], v[180:183], v[228:231], v[66:69]
	s_setprio 0
	s_barrier
	s_add_i32 s59, s59, s72
	v_lshl_add_u64 v[192:193], s[38:39], 0, v[0:1]
	s_mov_b32 m0, s59
	ds_read_b128 v[184:187], v207 offset:16384
	ds_read_b128 v[188:191], v207 offset:17408
	ds_read_b128 v[208:211], v207 offset:18432
	ds_read_b128 v[212:215], v207 offset:19456
	ds_read_b128 v[216:219], v207 offset:20480
	ds_read_b128 v[220:223], v207 offset:21504
	ds_read_b128 v[224:227], v207 offset:22528
	ds_read_b128 v[228:231], v207 offset:23552
	global_load_lds_dwordx4 v[192:193], off
	s_add_i32 m0, s59, 0x2000
	v_lshl_add_u64 v[194:195], s[38:39], 0, v[166:167]
	s_add_u32 s38, s38, s14
	s_addc_u32 s39, s39, 0
	s_add_i32 s59, s86, s72
	global_load_lds_dwordx4 v[194:195], off
	v_lshl_add_u64 v[232:233], s[38:39], 0, v[0:1]
	s_mov_b32 m0, s59
	v_lshl_add_u64 v[234:235], s[38:39], 0, v[166:167]
	global_load_lds_dwordx4 v[232:233], off
	s_add_i32 m0, s59, 0x2000
	v_lshl_add_u64 v[236:237], s[70:71], 0, v[170:171]
	global_load_lds_dwordx4 v[234:235], off
	s_mov_b32 m0, s73
	v_lshl_add_u64 v[238:239], s[70:71], 0, v[168:169]
	global_load_lds_dwordx4 v[236:237], off
	s_mov_b32 m0, s74
	s_nop 0
	global_load_lds_dwordx4 v[238:239], off
	s_waitcnt vmcnt(8)
	s_waitcnt lgkmcnt(0)
	s_setprio 1
	s_barrier
; #define PG8_STAGE(bufoff, gbase, voff) do { _Pragma("unroll") for (int _i = 0; _i < 2; ++_i) \
;         __builtin_amdgcn_global_load_lds((const unsigned*)((const char*)(gbase) + (voff)[_i]), (PG8_LAS unsigned*)(lds + (bufoff) + ldsw + _i * 8192), 16, 0, 0); } while (0)
; #define PG8_LDA(dst, b, h) do { _Pragma("unroll") for (int m = 0; m < 4; ++m) _Pragma("unroll") for (int k = 0; k < 2; ++k) dst[m][k] = *(const PG8_LAS bf16x8*)(lds + PG8_SA(b, h) + aoff + m * 2048 + k * 1024); } while (0)
; #define PG8_LDB(dst, b, h) do { _Pragma("unroll") for (int n = 0; n < 2; ++n) _Pragma("unroll") for (int k = 0; k < 2; ++k) dst[n][k] = *(const PG8_LAS bf16x8*)(lds + PG8_SB(b, h) + boff + n * 2048 + k * 1024); } while (0)
; #define PG8_MMA(ai, bj, At, Bt) do { __builtin_amdgcn_s_setprio(1); _Pragma("unroll") for (int m = 0; m < 4; ++m) _Pragma("unroll") for (int n = 0; n < 2; ++n) _Pragma("unroll") for (int k = 0; k < 2; ++k) \
;         acc[ai][bj][m][n] = __builtin_amdgcn_mfma_f32_16x16x32_bf16(Bt[n][k], At[m][k], acc[ai][bj][m][n], 0, 0, 0); __builtin_amdgcn_s_setprio(0); } while (0)
; #define PG8_WAIT_V(n) asm volatile("s_waitcnt vmcnt(" #n ")" ::: "memory")
; #define PG8_WAIT_L(n) asm volatile("s_waitcnt lgkmcnt(" #n ")" ::: "memory")
; #define PG8_BAR __builtin_amdgcn_s_barrier()
; #define PG8_SCHED __builtin_amdgcn_sched_barrier(0)
; template <class Epi, class Sched, bool ALIGN_EPI = false, bool SP2 = false>
; __device__ __forceinline__ void gemm_phase(PG8_LAS unsigned char* lds, const Gemm g, const Sched& S, const Epi& E, const int tid) {
;     ...
;             PG8_WAIT_V(8); PG8_WAIT_L(0); PG8_BAR; PG8_MMA(1, 0, At, B0); PG8_MMA(1, 1, At, B1); PG8_BAR; PG8_SCHED;
;             PG8_LDB(B0, 1, 0); PG8_LDB(B1, 1, 1); PG8_SCHED; PG8_LDA(At, 1, 0); PG8_STAGE(PG8_SA(0, 1), a2 + hstep, voffA);
;             PG8_WAIT_V(8); PG8_WAIT_L(0); PG8_BAR; PG8_MMA(0, 0, At, B0); PG8_MMA(0, 1, At, B1); PG8_BAR; PG8_SCHED;
	v_mfma_f32_16x16x32_bf16 v[62:65], v[130:133], v[184:187], v[62:65]
	v_mfma_f32_16x16x32_bf16 v[58:61], v[138:141], v[184:187], v[58:61]
	v_mfma_f32_16x16x32_bf16 v[46:49], v[130:133], v[208:211], v[46:49]
	v_mfma_f32_16x16x32_bf16 v[42:45], v[138:141], v[208:211], v[42:45]
	v_mfma_f32_16x16x32_bf16 v[30:33], v[130:133], v[216:219], v[30:33]
	v_mfma_f32_16x16x32_bf16 v[26:29], v[138:141], v[216:219], v[26:29]
	v_mfma_f32_16x16x32_bf16 v[14:17], v[130:133], v[224:227], v[14:17]
	v_mfma_f32_16x16x32_bf16 v[10:13], v[138:141], v[224:227], v[10:13]
	v_mfma_f32_16x16x32_bf16 v[62:65], v[134:137], v[188:191], v[62:65]
	v_mfma_f32_16x16x32_bf16 v[58:61], v[142:145], v[188:191], v[58:61]
	v_mfma_f32_16x16x32_bf16 v[46:49], v[134:137], v[212:215], v[46:49]
	v_mfma_f32_16x16x32_bf16 v[42:45], v[142:145], v[212:215], v[42:45]
	v_mfma_f32_16x16x32_bf16 v[30:33], v[134:137], v[220:223], v[30:33]
	v_mfma_f32_16x16x32_bf16 v[26:29], v[142:145], v[220:223], v[26:29]
	v_mfma_f32_16x16x32_bf16 v[14:17], v[134:137], v[228:231], v[14:17]
	v_mfma_f32_16x16x32_bf16 v[10:13], v[142:145], v[228:231], v[10:13]
	v_mfma_f32_16x16x32_bf16 v[54:57], v[146:149], v[184:187], v[54:57]
	v_mfma_f32_16x16x32_bf16 v[50:53], v[176:179], v[184:187], v[50:53]
	v_mfma_f32_16x16x32_bf16 v[38:41], v[146:149], v[208:211], v[38:41]
	v_mfma_f32_16x16x32_bf16 v[34:37], v[176:179], v[208:211], v[34:37]
	v_mfma_f32_16x16x32_bf16 v[22:25], v[146:149], v[216:219], v[22:25]
	v_mfma_f32_16x16x32_bf16 v[18:21], v[176:179], v[216:219], v[18:21]
	v_mfma_f32_16x16x32_bf16 v[6:9], v[146:149], v[224:227], v[6:9]
	v_mfma_f32_16x16x32_bf16 v[2:5], v[176:179], v[224:227], v[2:5]
	v_mfma_f32_16x16x32_bf16 v[54:57], v[150:153], v[188:191], v[54:57]
	v_mfma_f32_16x16x32_bf16 v[50:53], v[180:183], v[188:191], v[50:53]
	v_mfma_f32_16x16x32_bf16 v[38:41], v[150:153], v[212:215], v[38:41]
	v_mfma_f32_16x16x32_bf16 v[34:37], v[180:183], v[212:215], v[34:37]
	v_mfma_f32_16x16x32_bf16 v[22:25], v[150:153], v[220:223], v[22:25]
	v_mfma_f32_16x16x32_bf16 v[18:21], v[180:183], v[220:223], v[18:21]
	v_mfma_f32_16x16x32_bf16 v[6:9], v[150:153], v[228:231], v[6:9]
	v_mfma_f32_16x16x32_bf16 v[2:5], v[180:183], v[228:231], v[2:5]
	s_setprio 0
	s_barrier
	s_add_i32 s59, 0, 0x18000
	s_add_i32 s86, 0, 0x1c000
	v_add_u32_e32 v142, s59, v205
	v_add_u32_e32 v180, s86, v205
	ds_read_b128 v[130:133], v142
	ds_read_b128 v[134:137], v142 offset:1024
	ds_read_b128 v[138:141], v142 offset:2048
	ds_read_b128 v[142:145], v142 offset:3072
	ds_read_b128 v[146:149], v180
	ds_read_b128 v[150:153], v180 offset:1024
	ds_read_b128 v[176:179], v180 offset:2048
	ds_read_b128 v[180:183], v180 offset:3072
	s_add_u32 s38, s70, s14
	s_addc_u32 s39, s71, 0
	s_mov_b32 m0, s75
	v_lshl_add_u64 v[240:241], s[38:39], 0, v[170:171]
	ds_read_b128 v[184:187], v207 offset:32768
	ds_read_b128 v[188:191], v207 offset:33792
	ds_read_b128 v[208:211], v207 offset:34816
	ds_read_b128 v[212:215], v207 offset:35840
	ds_read_b128 v[216:219], v207 offset:36864
	ds_read_b128 v[220:223], v207 offset:37888
	ds_read_b128 v[224:227], v207 offset:38912
	ds_read_b128 v[228:231], v207 offset:39936
	global_load_lds_dwordx4 v[240:241], off
	v_lshl_add_u64 v[240:241], s[38:39], 0, v[168:169]
	s_mov_b32 m0, s76
	s_nop 0
	global_load_lds_dwordx4 v[240:241], off
	s_waitcnt vmcnt(8)
	s_waitcnt lgkmcnt(0)
	s_setprio 1
	s_barrier
	v_mfma_f32_16x16x32_bf16 v[126:129], v[130:133], v[184:187], v[126:129]
	v_mfma_f32_16x16x32_bf16 v[122:125], v[138:141], v[184:187], v[122:125]
	v_mfma_f32_16x16x32_bf16 v[110:113], v[130:133], v[208:211], v[110:113]
	v_mfma_f32_16x16x32_bf16 v[106:109], v[138:141], v[208:211], v[106:109]
	v_mfma_f32_16x16x32_bf16 v[94:97], v[130:133], v[216:219], v[94:97]
	v_mfma_f32_16x16x32_bf16 v[90:93], v[138:141], v[216:219], v[90:93]
	v_mfma_f32_16x16x32_bf16 v[78:81], v[130:133], v[224:227], v[78:81]
	v_mfma_f32_16x16x32_bf16 v[74:77], v[138:141], v[224:227], v[74:77]
	v_mfma_f32_16x16x32_bf16 v[126:129], v[134:137], v[188:191], v[126:129]
	v_mfma_f32_16x16x32_bf16 v[122:125], v[142:145], v[188:191], v[122:125]
	v_mfma_f32_16x16x32_bf16 v[110:113], v[134:137], v[212:215], v[110:113]
	v_mfma_f32_16x16x32_bf16 v[106:109], v[142:145], v[212:215], v[106:109]
	v_mfma_f32_16x16x32_bf16 v[94:97], v[134:137], v[220:223], v[94:97]
	v_mfma_f32_16x16x32_bf16 v[90:93], v[142:145], v[220:223], v[90:93]
	v_mfma_f32_16x16x32_bf16 v[78:81], v[134:137], v[228:231], v[78:81]
	v_mfma_f32_16x16x32_bf16 v[74:77], v[142:145], v[228:231], v[74:77]
	v_mfma_f32_16x16x32_bf16 v[118:121], v[146:149], v[184:187], v[118:121]
	v_mfma_f32_16x16x32_bf16 v[114:117], v[176:179], v[184:187], v[114:117]
	v_mfma_f32_16x16x32_bf16 v[102:105], v[146:149], v[208:211], v[102:105]
	v_mfma_f32_16x16x32_bf16 v[98:101], v[176:179], v[208:211], v[98:101]
	v_mfma_f32_16x16x32_bf16 v[86:89], v[146:149], v[216:219], v[86:89]
	v_mfma_f32_16x16x32_bf16 v[82:85], v[176:179], v[216:219], v[82:85]
	v_mfma_f32_16x16x32_bf16 v[70:73], v[146:149], v[224:227], v[70:73]
	v_mfma_f32_16x16x32_bf16 v[66:69], v[176:179], v[224:227], v[66:69]
	v_mfma_f32_16x16x32_bf16 v[118:121], v[150:153], v[188:191], v[118:121]
	v_mfma_f32_16x16x32_bf16 v[114:117], v[180:183], v[188:191], v[114:117]
	v_mfma_f32_16x16x32_bf16 v[102:105], v[150:153], v[212:215], v[102:105]
	v_mfma_f32_16x16x32_bf16 v[98:101], v[180:183], v[212:215], v[98:101]
	v_mfma_f32_16x16x32_bf16 v[86:89], v[150:153], v[220:223], v[86:89]
	v_mfma_f32_16x16x32_bf16 v[82:85], v[180:183], v[220:223], v[82:85]
	v_mfma_f32_16x16x32_bf16 v[70:73], v[150:153], v[228:231], v[70:73]
	v_mfma_f32_16x16x32_bf16 v[66:69], v[180:183], v[228:231], v[66:69]
	s_setprio 0
	s_barrier
; #define PG8_STAGE(bufoff, gbase, voff) do { _Pragma("unroll") for (int _i = 0; _i < 2; ++_i) \
;         __builtin_amdgcn_global_load_lds((const unsigned*)((const char*)(gbase) + (voff)[_i]), (PG8_LAS unsigned*)(lds + (bufoff) + ldsw + _i * 8192), 16, 0, 0); } while (0)
; #define PG8_LDA(dst, b, h) do { _Pragma("unroll") for (int m = 0; m < 4; ++m) _Pragma("unroll") for (int k = 0; k < 2; ++k) dst[m][k] = *(const PG8_LAS bf16x8*)(lds + PG8_SA(b, h) + aoff + m * 2048 + k * 1024); } while (0)
; #define PG8_MMA(ai, bj, At, Bt) do { __builtin_amdgcn_s_setprio(1); _Pragma("unroll") for (int m = 0; m < 4; ++m) _Pragma("unroll") for (int n = 0; n < 2; ++n) _Pragma("unroll") for (int k = 0; k < 2; ++k) \
;         acc[ai][bj][m][n] = __builtin_amdgcn_mfma_f32_16x16x32_bf16(Bt[n][k], At[m][k], acc[ai][bj][m][n], 0, 0, 0); __builtin_amdgcn_s_setprio(0); } while (0)
; #define PG8_WAIT_V(n) asm volatile("s_waitcnt vmcnt(" #n ")" ::: "memory")
; #define PG8_WAIT_L(n) asm volatile("s_waitcnt lgkmcnt(" #n ")" ::: "memory")
; #define PG8_BAR __builtin_amdgcn_s_barrier()
; #define PG8_SCHED __builtin_amdgcn_sched_barrier(0)
; template <class Epi, class Sched, bool ALIGN_EPI = false, bool SP2 = false>
; __device__ __forceinline__ void gemm_phase(PG8_LAS unsigned char* lds, const Gemm g, const Sched& S, const Epi& E, const int tid) {
;     ...
;             PG8_LDA(At, 1, 1); PG8_STAGE(PG8_SB(1, 0), b3, voffB); PG8_STAGE(PG8_SB(1, 1), b3 + hstep, voffB); PG8_STAGE(PG8_SA(1, 0), a3, voffA);
;             PG8_WAIT_V(8); PG8_WAIT_L(0); PG8_BAR; PG8_MMA(1, 0, At, B0); PG8_MMA(1, 1, At, B1); PG8_BAR; PG8_SCHED;
;     ...
;         if constexpr (ALIGN_EPI) { if (wr == 0) PG8_BAR; }
	s_add_i32 s38, s59, s72
	v_lshl_add_u64 v[192:193], v[192:193], 0, s[56:57]
	s_mov_b32 m0, s38
	ds_read_b128 v[184:187], v207 offset:49152
	ds_read_b128 v[188:191], v207 offset:50176
	ds_read_b128 v[208:211], v207 offset:51200
	ds_read_b128 v[212:215], v207 offset:52224
	ds_read_b128 v[216:219], v207 offset:53248
	ds_read_b128 v[220:223], v207 offset:54272
	ds_read_b128 v[224:227], v207 offset:55296
	ds_read_b128 v[228:231], v207 offset:56320
	global_load_lds_dwordx4 v[192:193], off
	v_lshl_add_u64 v[192:193], v[194:195], 0, s[56:57]
	s_add_i32 m0, s38, 0x2000
	s_add_i32 s38, s86, s72
	global_load_lds_dwordx4 v[192:193], off
	v_lshl_add_u64 v[192:193], v[232:233], 0, s[56:57]
	s_mov_b32 m0, s38
	s_nop 0
	global_load_lds_dwordx4 v[192:193], off
	v_lshl_add_u64 v[192:193], v[234:235], 0, s[56:57]
	s_add_i32 m0, s38, 0x2000
	s_nop 0
	global_load_lds_dwordx4 v[192:193], off
	v_lshl_add_u64 v[192:193], v[236:237], 0, s[56:57]
	s_mov_b32 m0, s79
	s_nop 0
	global_load_lds_dwordx4 v[192:193], off
	v_lshl_add_u64 v[192:193], v[238:239], 0, s[56:57]
	s_mov_b32 m0, s80
	s_nop 0
	global_load_lds_dwordx4 v[192:193], off
	s_waitcnt vmcnt(8)
	s_waitcnt lgkmcnt(0)
	s_setprio 1
	s_barrier
	v_mfma_f32_16x16x32_bf16 v[62:65], v[130:133], v[184:187], v[62:65]
	v_mfma_f32_16x16x32_bf16 v[58:61], v[138:141], v[184:187], v[58:61]
	v_mfma_f32_16x16x32_bf16 v[46:49], v[130:133], v[208:211], v[46:49]
	v_mfma_f32_16x16x32_bf16 v[42:45], v[138:141], v[208:211], v[42:45]
	v_mfma_f32_16x16x32_bf16 v[30:33], v[130:133], v[216:219], v[30:33]
	v_mfma_f32_16x16x32_bf16 v[26:29], v[138:141], v[216:219], v[26:29]
	v_mfma_f32_16x16x32_bf16 v[14:17], v[130:133], v[224:227], v[14:17]
	v_mfma_f32_16x16x32_bf16 v[10:13], v[138:141], v[224:227], v[10:13]
	v_mfma_f32_16x16x32_bf16 v[62:65], v[134:137], v[188:191], v[62:65]
	v_mfma_f32_16x16x32_bf16 v[58:61], v[142:145], v[188:191], v[58:61]
	v_mfma_f32_16x16x32_bf16 v[46:49], v[134:137], v[212:215], v[46:49]
	v_mfma_f32_16x16x32_bf16 v[42:45], v[142:145], v[212:215], v[42:45]
	v_mfma_f32_16x16x32_bf16 v[30:33], v[134:137], v[220:223], v[30:33]
	v_mfma_f32_16x16x32_bf16 v[26:29], v[142:145], v[220:223], v[26:29]
	v_mfma_f32_16x16x32_bf16 v[14:17], v[134:137], v[228:231], v[14:17]
	v_mfma_f32_16x16x32_bf16 v[10:13], v[142:145], v[228:231], v[10:13]
	v_mfma_f32_16x16x32_bf16 v[54:57], v[146:149], v[184:187], v[54:57]
	v_mfma_f32_16x16x32_bf16 v[50:53], v[176:179], v[184:187], v[50:53]
	v_mfma_f32_16x16x32_bf16 v[38:41], v[146:149], v[208:211], v[38:41]
	v_mfma_f32_16x16x32_bf16 v[34:37], v[176:179], v[208:211], v[34:37]
	v_mfma_f32_16x16x32_bf16 v[22:25], v[146:149], v[216:219], v[22:25]
	v_mfma_f32_16x16x32_bf16 v[18:21], v[176:179], v[216:219], v[18:21]
	v_mfma_f32_16x16x32_bf16 v[6:9], v[146:149], v[224:227], v[6:9]
	v_mfma_f32_16x16x32_bf16 v[2:5], v[176:179], v[224:227], v[2:5]
	v_mfma_f32_16x16x32_bf16 v[54:57], v[150:153], v[188:191], v[54:57]
	v_mfma_f32_16x16x32_bf16 v[50:53], v[180:183], v[188:191], v[50:53]
	v_mfma_f32_16x16x32_bf16 v[38:41], v[150:153], v[212:215], v[38:41]
	v_mfma_f32_16x16x32_bf16 v[34:37], v[180:183], v[212:215], v[34:37]
	v_mfma_f32_16x16x32_bf16 v[22:25], v[150:153], v[220:223], v[22:25]
	v_mfma_f32_16x16x32_bf16 v[18:21], v[180:183], v[220:223], v[18:21]
	v_mfma_f32_16x16x32_bf16 v[6:9], v[150:153], v[228:231], v[6:9]
	v_mfma_f32_16x16x32_bf16 v[2:5], v[180:183], v[228:231], v[2:5]
	s_setprio 0
	s_barrier
	s_add_u32 s68, s68, 0x100
	s_addc_u32 s69, s69, 0
	s_add_u32 s50, s50, 0x100
	s_addc_u32 s51, s51, 0
	s_cmp_ge_u32 s85, s78
	s_mov_b32 s70, s85
	s_cbranch_scc0 .LBB0_618
	s_and_b64 vcc, exec, s[22:23]
	s_cbranch_vccz .LBB0_621
	s_barrier
